# v14_split124
# speedup vs baseline: 1.0195x; 1.0195x over previous
; __device__ __forceinline__ int otid() { int t = threadIdx.x; asm volatile("" : "+v"(t)); return t; }
; __device__ __forceinline__ void p2_gemm1(const Params& p, int layer, char* shm, int stage) {
;   constexpr int per = GRID >> 3, R = GRID;
;   constexpr int nd = p2_deferred();
;   constexpr int nfull = nd ? P2_T / R : (P2_T + R - 1) / R;
;   const int me = (blockIdx.x & 7) * per + (blockIdx.x >> 3);
;   const int r0 = stage ? nfull : 0, r1 = stage ? (nd ? nfull + 1 : nfull) : nfull;
;   for (int round = r0; round < r1; ++round) {
;     const int idx = stage ? nfull * R + me : (round * 8 + (blockIdx.x & 7)) * per + (blockIdx.x >> 3);
;     if (idx >= P2_T) break;
;     p2_one_tile(p, layer, idx, shm);
;   }
; }
; __device__ __forceinline__ void p3_prep(const Params& p, int layer, float* smf) {
;   const int T = otid(), hb = T >> 8, tid = T & 255, lane = T & 63, wave = (T >> 6) & 3;
;   const int N_TOK = NTOK / 4, N_VA = 4 * 43 * 4, N_VD = 4 * 43 * 16, N_U = 4 * 43 * 48;
;   const int N_TRP = (N_VA + N_VD + N_U) / 2;
;   const int total = N_TOK + N_TRP;
;   constexpr int nd = p2_deferred();
;   const int me = (blockIdx.x & 7) * (GRID >> 3) + (blockIdx.x >> 3);
;   const bool gblk = me < nd;
;   constexpr int nslots = nd + 2 * (GRID - nd);
;   const int slot0 = gblk ? me : nd + 2 * (me - nd);
;   const int myslots = gblk ? 1 : 2;
;   for (int sl = 0; sl < myslots; ++sl)
;   for (int it = slot0 + sl; it < total; it += nslots) {
.LBB0_196:
	s_or_b64 exec, exec, s[0:1]
	s_add_u32 s40, s38, 0x30c00000
	v_readlane_b32 s0, v253, 7
	s_addc_u32 s41, s39, 0
	v_readlane_b32 s4, v253, 11
	v_readlane_b32 s1, v253, 8
	v_readlane_b32 s5, v253, 12
	s_add_u32 s0, s4, 0x4000
	s_addc_u32 s1, s5, 0
	s_add_u32 s44, s38, 0x12a80000
	v_readlane_b32 s2, v253, 9
	v_readlane_b32 s3, v253, 10
	v_readlane_b32 s6, v253, 13
	v_readlane_b32 s7, v253, 14
	v_readlane_b32 s8, v253, 15
	v_readlane_b32 s9, v253, 16
	v_readlane_b32 s10, v253, 17
	v_readlane_b32 s11, v253, 18
	v_readlane_b32 s12, v253, 19
	v_readlane_b32 s13, v253, 20
	v_readlane_b32 s14, v253, 21
	v_readlane_b32 s15, v253, 22
	v_writelane_b32 v253, s0, 59
	s_addc_u32 s45, s39, 0
	v_mbcnt_hi_u32_b32 v157, -1, v102
	v_writelane_b32 v253, s1, 60
	s_add_u32 s0, s38, 0x41542a00
	s_addc_u32 s1, s39, 0
	v_writelane_b32 v253, s0, 61
	v_and_b32_e32 v0, 64, v157
	s_movk_i32 s59, 0x100
	v_writelane_b32 v253, s1, 62
	s_add_u32 s0, s38, 0x41545c00
	s_addc_u32 s1, s39, 0
	v_writelane_b32 v253, s0, 63
	v_mov_b32_e32 v100, 1
	v_mov_b32_e32 v1, 0
	v_writelane_b32 v254, s1, 0
	s_add_u32 s0, s38, 0x41545d00
	s_addc_u32 s1, s39, 0
	v_writelane_b32 v254, s0, 1
	v_mov_b32_e32 v134, 0x358637bd
	v_mov_b32_e32 v156, 1
	v_writelane_b32 v254, s1, 2
	s_lshl_b32 s0, s61, 5
	s_and_b32 s33, s0, 0xe0
	s_lshr_b32 s0, s61, 3
	s_add_i32 s33, s33, s0
	s_add_u32 s62, s38, 0x16c80000
	s_addc_u32 s63, s39, 0
	s_sub_i32 s2, s33, 124
	s_cmpk_gt_u32 s33, 123
	s_cselect_b64 s[0:1], -1, 0
	v_writelane_b32 v254, s0, 3
	v_add_u32_e32 v158, 64, v0
	v_xor_b32_e32 v159, 32, v157
	v_writelane_b32 v254, s1, 4
	s_and_b64 s[0:1], s[0:1], exec
	s_cselect_b32 s0, s2, 0x4000
	v_writelane_b32 v254, s0, 5
	s_add_u32 s0, s38, 0x28800000
	s_addc_u32 s1, s39, 0
	v_writelane_b32 v254, s0, 6
	v_xor_b32_e32 v160, 16, v157
	v_xor_b32_e32 v161, 8, v157
	v_writelane_b32 v254, s1, 7
	s_add_u32 s0, s38, 0x27780000
	s_addc_u32 s1, s39, 0
	v_writelane_b32 v254, s0, 8
	v_xor_b32_e32 v162, 4, v157
	v_xor_b32_e32 v163, 2, v157
	v_writelane_b32 v254, s1, 9
	s_add_u32 s0, s38, 0x250e0000
	s_addc_u32 s1, s39, 0
	v_writelane_b32 v254, s0, 10
	v_xor_b32_e32 v164, 1, v157
	v_mov_b32_e32 v136, 0x1fff0
	v_writelane_b32 v254, s1, 11
	s_add_u32 s0, s38, 0x26700000
	s_addc_u32 s1, s39, 0
	v_writelane_b32 v254, s0, 12
	v_mov_b32_e32 v166, 0x3f300000
	v_mov_b32_e32 v167, 0x39000000
	v_writelane_b32 v254, s1, 13
	s_add_u32 s0, s38, 0x25500000
	s_addc_u32 s1, s39, 0
	v_writelane_b32 v254, s0, 14
	s_mov_b32 s88, 0x800000
	s_movk_i32 s89, 0x900
	v_writelane_b32 v254, s1, 15
	s_add_u32 s0, s38, 0x23ac0000
	s_addc_u32 s1, s39, 0
	s_add_u32 s96, s38, 0x41400000
	s_addc_u32 s97, s39, 0
	s_add_u32 s42, s38, 0x41502000
	v_writelane_b32 v254, s0, 16
	s_addc_u32 s43, s39, 0
	s_mov_b32 s94, 0xffff0
	v_writelane_b32 v254, s1, 17
	s_add_u32 s0, s38, 0x2b980000
	s_addc_u32 s1, s39, 0
	v_writelane_b32 v254, s0, 18
	s_mov_b32 s95, 0x10000
	s_mov_b32 s48, 0x14000
	v_writelane_b32 v254, s1, 19
	s_add_u32 s0, s38, 0x41545e00
	v_writelane_b32 v254, s0, 20
	s_addc_u32 s0, s39, 0
	v_writelane_b32 v254, s0, 21
	s_add_u32 s0, s38, 0x10800000
	s_addc_u32 s1, s39, 0
	v_writelane_b32 v254, s0, 22
	s_mov_b32 s49, 0x18000
	s_mov_b32 s36, 0x1c000
	v_writelane_b32 v254, s1, 23
	s_add_u32 s0, s38, 0x10900000
	s_addc_u32 s1, s39, 0
	v_writelane_b32 v254, s0, 24
	s_movk_i32 s37, 0x6400
	s_movk_i32 s90, 0xffc0
	v_writelane_b32 v254, s1, 25
	s_add_u32 s0, s38, 0x3f300000
	s_addc_u32 s1, s39, 0
	v_writelane_b32 v254, s0, 26
	s_movk_i32 s91, 0x7fff
	s_movk_i32 s69, 0x810
	v_writelane_b32 v254, s1, 27
	s_add_u32 s0, s38, 0x24cc0000
	s_addc_u32 s1, s39, 0
	v_writelane_b32 v254, s0, 28
	s_movk_i32 s66, 0x1080
	s_mov_b32 s67, 0xfe03f81
	v_writelane_b32 v254, s1, 29
	s_add_u32 s0, s38, 0x39000000
	s_addc_u32 s1, s39, 0
	v_writelane_b32 v254, s0, 30
	s_movk_i32 s52, 0x840
	s_mov_b32 s53, 0x3e0293ee
	v_writelane_b32 v254, s1, 31
	s_add_u32 s0, s38, 0x3b100000
	s_addc_u32 s1, s39, 0
	v_writelane_b32 v254, s0, 32
	s_mov_b32 s68, 0
	s_mov_b64 s[4:5], 0
	v_writelane_b32 v254, s1, 33
	s_add_u32 s0, s38, 0x3d200000
	s_addc_u32 s1, s39, 0
	v_writelane_b32 v254, s0, 34
	s_mov_b64 s[56:57], 0x80
	s_mov_b64 s[70:71], 0x16c82200
	v_writelane_b32 v254, s1, 35
	s_add_u32 s0, s38, 0x2ca00000
	s_addc_u32 s1, s39, 0
	v_writelane_b32 v254, s0, 36
	s_brev_b32 s58, 60
	s_mov_b64 s[92:93], 0x16c82400
	v_writelane_b32 v254, s1, 37
	s_lshl_b32 s0, s61, 9
	v_writelane_b32 v254, s0, 38
	s_and_b32 s1, s61, 7
	v_readlane_b32 s0, v253, 0
	v_writelane_b32 v254, s1, 39
	s_ashr_i32 s1, s61, 3
	s_lshl_b32 s22, s0, 9
	v_writelane_b32 v254, s1, 40
	s_lshr_b32 s1, s0, 3
	v_writelane_b32 v254, s1, 41
	s_add_u32 s1, s38, 0xc800000
	v_writelane_b32 v254, s1, 42
	s_addc_u32 s1, s39, 0
	s_cmpk_lt_i32 s61, 0x100
	v_writelane_b32 v254, s1, 43
	s_cselect_b64 s[2:3], -1, 0
	v_writelane_b32 v254, s2, 44
	s_add_u32 s1, s38, 0x30a00000
	s_nop 0
	v_writelane_b32 v254, s3, 45
	v_writelane_b32 v254, s1, 46
	s_addc_u32 s1, s39, 0
	v_writelane_b32 v254, s1, 47
	s_lshl_b32 s1, s61, 11
	v_writelane_b32 v254, s1, 48
	s_lshl_b32 s1, s61, 4
	v_writelane_b32 v254, s1, 49
	s_lshl_b32 s1, s0, 4
	v_writelane_b32 v254, s1, 50
	v_writelane_b32 v254, s61, 51
	s_lshl_b32 s1, s61, 8
	s_ashr_i32 s29, s28, 31
	v_writelane_b32 v254, s1, 52
	s_lshl_b32 s0, s0, 8
	v_writelane_b32 v254, s0, 53
	s_lshl_b64 s[0:1], s[28:29], 13
	v_writelane_b32 v254, s0, 54
	s_lshl_b64 s[16:17], s[28:29], 14
	s_mov_b64 s[2:3], 0x100
	v_writelane_b32 v254, s1, 55
	s_mov_b32 s0, s28
	v_writelane_b32 v254, s0, 56
	s_barrier
	s_nop 0
	v_writelane_b32 v254, s1, 57
	s_mov_b32 s1, 0
	v_writelane_b32 v254, s0, 58
	s_nop 1
	v_writelane_b32 v254, s1, 59
	v_writelane_b32 v254, s16, 60
	s_mov_b64 s[0:1], -1
	s_nop 0
	v_writelane_b32 v254, s17, 61
	v_writelane_b32 v254, s22, 62
	s_branch .LBB0_199

; __device__ __forceinline__ void p2_gemm1(const Params& p, int layer, char* shm, int stage) {
;   constexpr int per = GRID >> 3, R = GRID;
;   constexpr int nd = p2_deferred();
;   constexpr int nfull = nd ? P2_T / R : (P2_T + R - 1) / R;
;   const int me = (blockIdx.x & 7) * per + (blockIdx.x >> 3);
;   const int r0 = stage ? nfull : 0, r1 = stage ? (nd ? nfull + 1 : nfull) : nfull;
;   for (int round = r0; round < r1; ++round) {
;     const int idx = stage ? nfull * R + me : (round * 8 + (blockIdx.x & 7)) * per + (blockIdx.x >> 3);
;     if (idx >= P2_T) break;
;     p2_one_tile(p, layer, idx, shm);
;   }
; }
.LBB0_246:
	s_xor_b64 s[6:7], s[8:9], -1
	s_and_b64 s[0:1], s[8:9], exec
	s_cselect_b32 s4, 5, 8
	s_cselect_b32 s5, 0, 5
	s_waitcnt vmcnt(0)
	s_branch .LBB0_249

; __device__ __forceinline__ bool rid_map(int rid, int nM, int nN, int& mt, int& nt) {
;   if (rid >= nM * nN) return false;
;   constexpr int WGM = 4;
;   const int nig = WGM * nN, gid = rid / nig, fm = gid * WGM, gsz = min(nM - fm, WGM);
;   mt = fm + ((rid % nig) % gsz);
;   nt = (rid % nig) / gsz;
;   return true;
; }
; __device__ __forceinline__ void p2_gemm1(const Params& p, int layer, char* shm, int stage) {
;   constexpr int per = GRID >> 3, R = GRID;
;   constexpr int nd = p2_deferred();
;   constexpr int nfull = nd ? P2_T / R : (P2_T + R - 1) / R;
;   const int me = (blockIdx.x & 7) * per + (blockIdx.x >> 3);
;   const int r0 = stage ? nfull : 0, r1 = stage ? (nd ? nfull + 1 : nfull) : nfull;
;   for (int round = r0; round < r1; ++round) {
;     const int idx = stage ? nfull * R + me : (round * 8 + (blockIdx.x & 7)) * per + (blockIdx.x >> 3);
;     if (idx >= P2_T) break;
;     p2_one_tile(p, layer, idx, shm);
;   }
; }
.LBB0_249:
	s_lshl_b32 s10, s5, 8
	s_and_b64 s[0:1], s[8:9], exec
	s_cbranch_scc1 .Lmy_idx_st0
	s_mul_i32 s10, s5, 124
	s_addk_i32 s10, 660
	s_cmpk_lt_u32 s33, 124
	s_cselect_b32 s10, s10, 0x4000
.Lmy_idx_st0:
	s_add_i32 s10, s33, s10
	s_cmpk_gt_u32 s10, 0x671
	s_mov_b64 s[0:1], -1
	s_cbranch_scc1 .LBB0_248
	s_cmpk_gt_u32 s10, 0x461
	s_cbranch_scc0 .LBB0_252
	s_add_i32 s0, s10, 0xfffffb9e
	s_lshr_b32 s1, s0, 4
	s_and_b32 s11, s1, 0xffc
	s_sub_i32 s1, 33, s11
	s_min_u32 s12, s1, 4
	v_cvt_f32_ubyte0_e32 v2, s12
	v_rcp_iflag_f32_e32 v3, v2
	s_and_b32 s13, s0, 63
	v_cvt_f32_ubyte0_e32 v0, s13
	v_mul_f32_e32 v3, v0, v3
	v_trunc_f32_e32 v3, v3
	v_fma_f32 v0, -v3, v2, v0
	v_cvt_u32_f32_e32 v3, v3
	v_cmp_ge_f32_e64 vcc, |v0|, v2
	s_nop 1
	v_addc_co_u32_e64 v0, s[0:1], 0, v3, vcc
	v_mul_lo_u32 v0, v0, s12
	v_sub_u32_e32 v0, s13, v0
	v_add_u32_sdwa v0, s11, v0 dst_sel:DWORD dst_unused:UNUSED_PAD src0_sel:DWORD src1_sel:BYTE_0
	v_addc_co_u32_e32 v2, vcc, 34, v3, vcc
	s_cbranch_execz .LBB0_253
	s_branch .LBB0_254

; __device__ __forceinline__ void p3_prep(const Params& p, int layer, float* smf) {
;     ...
;   constexpr int nslots = nd + 2 * (GRID - nd);
;   const int slot0 = gblk ? me : nd + 2 * (me - nd);
;   const int myslots = gblk ? 1 : 2;
;   for (int sl = 0; sl < myslots; ++sl)
;   for (int it = slot0 + sl; it < total; it += nslots) {
.LBB0_305:
	v_readlane_b32 s0, v254, 3
	v_readlane_b32 s1, v254, 4
	s_mov_b64 s[4:5], 0
	s_mov_b32 s0, 1
	s_andn2_b64 vcc, exec, s[4:5]
	s_mov_b64 s[30:31], 0
	s_cbranch_vccnz .LBB0_401

; __device__ __forceinline__ void p3_prep(const Params& p, int layer, float* smf) {
;     ...
;   for (int sl = 0; sl < myslots; ++sl)
;   for (int it = slot0 + sl; it < total; it += nslots) {
;     int i = it;
;     if (i < N_TOK) {
;       int rows[2], bs[2], ts[2];
; #pragma unroll
;       for (int r = 0; r < 2; ++r) { rows[r] = 4 * i + 2 * hb + r; bs[r] = rows[r] / L; ts[r] = rows[r] % L; }
.LBB0_310:
	s_add_i32 s0, s54, 0x84
	v_add_u32_e32 v93, 0x108, v93
	v_add_u32_e32 v46, 0x210, v46
	s_cmpk_gt_i32 s54, 0x1e63
	s_mov_b32 s54, s0
	s_cbranch_scc1 .LBB0_305

; __device__ __forceinline__ void hyena_item(const Params& p, int layer, int c, bf16_t* sm) {
;     ...
; #pragma unroll
;       for (int i = 0; i < 5; ++i) {
;         int k = tid + 512 * i;
;         if (k < GTW / 2) {
;           ((unsigned*)(smc + hy_copy_base(1)))[k] = (rr[i][0] >> 16) | (rr[i][1] << 16);
;           ((unsigned*)(smc + hy_copy_base(2)))[k] = rr[i][1];
;           ((unsigned*)(smc + hy_copy_base(3)))[k] = (rr[i][1] >> 16) | (rr[i][2] << 16);
;           ((unsigned*)(smc + hy_copy_base(4)))[k] = rr[i][2];
;           ((unsigned*)(smc + hy_copy_base(5)))[k] = (rr[i][2] >> 16) | (rr[i][3] << 16);
;           ((unsigned*)(smc + hy_copy_base(6)))[k] = rr[i][3];
;           ((unsigned*)(smc + hy_copy_base(7)))[k] = (rr[i][3] >> 16) | (rr[i][4] << 16);
;         }
;       }
.LBB0_509:
	s_or_b64 exec, exec, s[0:1]
	v_add_u32_e32 v152, 0x114d0, v132
	v_add_u32_e32 v149, 0x136e0, v132
	s_and_saveexec_b64 s[0:1], s[16:17]
	s_cbranch_execz .LBB0_511
	s_mov_b32 s4, 0x1000706
	s_waitcnt lgkmcnt(1)
	v_perm_b32 v0, v133, v84, s4
	ds_write_b32 v132, v0 offset:27184
	ds_write_b32 v132, v84 offset:35904
	v_perm_b32 v0, v84, v85, s4
	ds_write_b32 v132, v0 offset:44656
	ds_write_b32 v132, v85 offset:53376
	s_waitcnt lgkmcnt(4)
	v_perm_b32 v0, v85, v82, s4
	ds_write_b32 v132, v0 offset:62112
	ds_write_b32 v152, v82
	v_perm_b32 v0, v82, v83, s4
	ds_write_b32 v149, v0
.LBB0_511:
	s_or_b64 exec, exec, s[0:1]
	v_lshlrev_b32_e32 v0, 2, v22
	v_add_u32_e32 v155, 0x114d0, v0
	v_add_u32_e32 v153, 0x136e0, v0
	s_and_saveexec_b64 s[0:1], s[18:19]
	s_cbranch_execz .LBB0_513
	s_mov_b32 s4, 0x1000706
	s_waitcnt lgkmcnt(1)
	v_perm_b32 v0, v138, v88, s4
	ds_write_b32 v132, v0 offset:29232
	ds_write_b32 v132, v88 offset:37952
	v_perm_b32 v0, v88, v89, s4
	ds_write_b32 v132, v0 offset:46704
	ds_write_b32 v132, v89 offset:55424
	s_waitcnt lgkmcnt(4)
	v_perm_b32 v0, v89, v86, s4
	ds_write_b32 v132, v0 offset:64160
	ds_write_b32 v155, v86
	v_perm_b32 v0, v86, v87, s4
	ds_write_b32 v153, v0
.LBB0_513:
	s_or_b64 exec, exec, s[0:1]
	v_lshlrev_b32_e32 v171, 2, v26
	v_add_u32_e32 v172, 0x114d0, v171
	v_add_u32_e32 v170, 0x136e0, v171
	s_and_saveexec_b64 s[0:1], s[20:21]
	s_cbranch_execz .LBB0_515
	s_mov_b32 s4, 0x1000706
	s_waitcnt lgkmcnt(1)
	v_perm_b32 v0, v139, v92, s4
	ds_write_b32 v132, v0 offset:31280
	ds_write_b32 v132, v92 offset:40000
	v_perm_b32 v0, v92, v93, s4
	ds_write_b32 v132, v0 offset:48752
	ds_write_b32 v132, v93 offset:57472
	s_waitcnt lgkmcnt(4)
	v_perm_b32 v0, v93, v90, s4
	ds_write_b32 v171, v0 offset:62112
	ds_write_b32 v172, v90
	v_perm_b32 v0, v90, v91, s4
	ds_write_b32 v170, v0
.LBB0_515:
	s_or_b64 exec, exec, s[0:1]
	v_add_u32_e32 v0, 0x600, v114
	v_lshlrev_b32_e32 v174, 2, v0
	v_add_u32_e32 v175, 0x114d0, v174
	v_add_u32_e32 v173, 0x136e0, v174
	s_and_saveexec_b64 s[0:1], s[22:23]
	s_cbranch_execz .LBB0_517
	s_mov_b32 s4, 0x1000706
	s_waitcnt lgkmcnt(1)
	v_perm_b32 v0, v140, v96, s4
	ds_write_b32 v132, v0 offset:33328
	ds_write_b32 v132, v96 offset:42048
	v_perm_b32 v0, v96, v97, s4
	ds_write_b32 v132, v0 offset:50800
	ds_write_b32 v132, v97 offset:59520
	s_waitcnt lgkmcnt(4)
	v_perm_b32 v0, v97, v94, s4
	ds_write_b32 v174, v0 offset:62112
	ds_write_b32 v175, v94
	v_perm_b32 v0, v94, v95, s4
	ds_write_b32 v173, v0
.LBB0_517:
	s_or_b64 exec, exec, s[0:1]
	v_add_u32_e32 v0, 0x800, v114
	v_lshlrev_b32_e32 v177, 2, v0
	v_add_u32_e32 v178, 0x114d0, v177
	v_add_u32_e32 v176, 0x136e0, v177
	s_and_saveexec_b64 s[0:1], s[24:25]
	s_cbranch_execz .LBB0_519
	s_mov_b32 s4, 0x1000706
	s_waitcnt lgkmcnt(1)
	v_perm_b32 v0, v141, v100, s4
	ds_write_b32 v132, v0 offset:35376
	ds_write_b32 v132, v100 offset:44096
	v_perm_b32 v0, v100, v101, s4
	ds_write_b32 v132, v0 offset:52848
	ds_write_b32 v132, v101 offset:61568
	s_waitcnt lgkmcnt(4)
	v_perm_b32 v0, v101, v98, s4
	ds_write_b32 v177, v0 offset:62112
	ds_write_b32 v178, v98
	v_perm_b32 v0, v98, v99, s4
	ds_write_b32 v176, v0

; #define HY_LOAD(AF, BF, i) do { const int dp_ = 64 - 32 * (i); \
;       BF = *(const bf16x8*)(zfrag - dp_); \
;       _Pragma("unroll") for (int tt = 0; tt < 4; ++tt) AF[tt] = *(const bf16x8*)(abase - (dp_ + 64 * (wave + 8 * tt)) * 2); \
;       if (has5) AF[4] = *(const bf16x8*)(abase - (dp_ + 64 * 32) * 2); } while (0)
; __device__ __forceinline__ void hyena_item(const Params& p, int layer, int c, bf16_t* sm) {
;     ...
;   const int s0c = (8 - (l15 & 7)) & 7;
;   const char* abase = smc + hy_copy_base(s0c) + (GTC - l15 + 8 * quad - s0c) * 2;
;   const bf16_t* zfrag = zb + (l15 & 3) * ZS + ZM + 16 * (l15 >> 2) + 8 * quad;
;   const int ob = l15 & 3, ot = 16 * (l15 >> 2) + quad * 4;
;     ...
;     bf16x8 a0[5], a1[5], b0, b1;
;     a0[4] = bf16x8{0, 0, 0, 0, 0, 0, 0, 0}; a1[4] = a0[4];
;     HY_LOAD(a0, b0, 0);
.LBB0_543:
	s_or_b64 exec, exec, s[0:1]
	v_sub_u32_e32 v0, 0, v114
	v_and_b32_e32 v0, 7, v0
	v_and_b32_e32 v14, 15, v114
	v_cmp_ne_u32_e32 vcc, 0, v0
	v_add_u32_e32 v21, v0, v14
	v_mul_u32_u24_e32 v15, 0x2200, v0
	v_lshlrev_b32_e32 v2, 2, v0
	v_mov_b32_e32 v20, 0xeda87430
	v_lshrrev_b32_e32 v20, v2, v20
	v_and_b32_e32 v20, 15, v20
	v_lshlrev_b32_e32 v20, 4, v20
	v_lshlrev_b32_e32 v2, 3, v13
	v_sub_u32_e32 v0, v2, v21
	v_lshlrev_b32_e32 v0, 1, v0
	v_add3_u32 v186, v20, v15, v0
	v_lshlrev_b32_e32 v0, 3, v114
	v_mul_u32_u24_e32 v128, 0x11a0, v12
	v_and_b32_e32 v0, 0x60, v0
	v_lshlrev_b32_e32 v13, 4, v13
	v_add3_u32 v187, v128, v0, v13
	v_not_b32_e32 v0, v114
	v_lshlrev_b32_e32 v0, 1, v0
	v_and_b32_e32 v0, 0xffffff80, v0
	v_add_u32_e32 v188, v186, v0
	s_waitcnt lgkmcnt(0)
	s_barrier
	ds_read_b128 v[40:43], v188 offset:22720
	ds_read_b128 v[36:39], v188 offset:21696
	ds_read_b128 v[28:31], v188 offset:20672
	ds_read_b128 v[24:27], v187 offset:64
	ds_read_b128 v[32:35], v188 offset:19648
	v_mov_b32_e32 v2, v1
	v_mov_b32_e32 v3, v1
	v_mov_b32_e32 v0, v1
	v_mov_b64_e32 v[18:19], v[2:3]
	v_cmp_gt_u32_e32 vcc, 64, v114
	v_mov_b64_e32 v[16:17], v[0:1]
	s_and_saveexec_b64 s[0:1], vcc
	ds_read_b128 v[16:19], v186 offset:18496
	s_or_b64 exec, exec, s[0:1]
	v_mul_u32_u24_e32 v115, 0x810, v12
	v_add3_u32 v12, v20, v15, v13
	v_lshlrev_b32_e32 v15, 1, v21
	v_sub_u32_e32 v12, v12, v15
	v_add_u32_e32 v129, 0x4880, v12
	v_lshlrev_b32_e32 v12, 3, v14
	v_and_b32_e32 v12, 0x60, v12
	v_add_u32_e32 v12, v128, v12
	s_movk_i32 s0, 0x80
	v_add3_u32 v130, v12, v13, s0
	v_lshlrev_b32_e32 v12, 1, v114
	v_and_b32_e32 v12, 0xffffff80, v12
	v_mov_b32_e32 v44, 0
	v_mov_b64_e32 v[22:23], v[2:3]
	v_ashrrev_i32_e32 v117, 31, v116
	v_sub_u32_e32 v131, 0, v12
	s_mov_b32 s4, -2
	v_mov_b32_e32 v107, v130
	v_mov_b32_e32 v109, v129
	v_mov_b64_e32 v[20:21], v[0:1]
	v_mov_b32_e32 v45, v44
	v_mov_b32_e32 v46, v44
	v_mov_b32_e32 v47, v44
	v_mov_b32_e32 v56, v44
	v_mov_b32_e32 v57, v44
	v_mov_b32_e32 v58, v44
	v_mov_b32_e32 v59, v44
	v_mov_b32_e32 v52, v44
	v_mov_b32_e32 v53, v44
	v_mov_b32_e32 v54, v44
	v_mov_b32_e32 v55, v44
	v_mov_b32_e32 v48, v44
	v_mov_b32_e32 v49, v44
	v_mov_b32_e32 v50, v44
	v_mov_b32_e32 v51, v44
	v_mov_b32_e32 v12, v44
	v_mov_b32_e32 v13, v44
	v_mov_b32_e32 v14, v44
	v_mov_b32_e32 v15, v44
	s_branch .LBB0_547

; __device__ __forceinline__ void hyena_item(const Params& p, int layer, int c, bf16_t* sm) {
;     ...
; #pragma unroll
;       for (int i = 0; i < 5; ++i) {
;         int k = tid + 512 * i;
;         if (k < GTW / 2) {
;           ((unsigned*)(smc + hy_copy_base(1)))[k] = (rr[i][0] >> 16) | (rr[i][1] << 16);
;           ((unsigned*)(smc + hy_copy_base(2)))[k] = rr[i][1];
;           ((unsigned*)(smc + hy_copy_base(3)))[k] = (rr[i][1] >> 16) | (rr[i][2] << 16);
;           ((unsigned*)(smc + hy_copy_base(4)))[k] = rr[i][2];
;           ((unsigned*)(smc + hy_copy_base(5)))[k] = (rr[i][2] >> 16) | (rr[i][3] << 16);
;           ((unsigned*)(smc + hy_copy_base(6)))[k] = rr[i][3];
;           ((unsigned*)(smc + hy_copy_base(7)))[k] = (rr[i][3] >> 16) | (rr[i][4] << 16);
;         }
;       }
.LBB0_586:
	s_mov_b32 s4, 0x1000706
	s_waitcnt vmcnt(0) lgkmcnt(1)
	v_perm_b32 v0, v141, v100, s4
	ds_write_b32 v132, v0 offset:35376
	ds_write_b32 v132, v100 offset:44096
	v_perm_b32 v0, v100, v101, s4
	ds_write_b32 v132, v0 offset:52848
	ds_write_b32 v132, v101 offset:61568
	s_waitcnt lgkmcnt(4)
	v_perm_b32 v0, v101, v98, s4
	ds_write_b32 v177, v0 offset:62112
	ds_write_b32 v178, v98
	v_perm_b32 v0, v98, v99, s4
	ds_write_b32 v176, v0

; __device__ __forceinline__ void hyena_item(const Params& p, int layer, int c, bf16_t* sm) {
;     ...
; #pragma unroll
;       for (int i = 0; i < 5; ++i) {
;         int k = tid + 512 * i;
;         if (k < GTW / 2) {
;           ((unsigned*)(smc + hy_copy_base(1)))[k] = (rr[i][0] >> 16) | (rr[i][1] << 16);
;           ((unsigned*)(smc + hy_copy_base(2)))[k] = rr[i][1];
;           ((unsigned*)(smc + hy_copy_base(3)))[k] = (rr[i][1] >> 16) | (rr[i][2] << 16);
;           ((unsigned*)(smc + hy_copy_base(4)))[k] = rr[i][2];
;           ((unsigned*)(smc + hy_copy_base(5)))[k] = (rr[i][2] >> 16) | (rr[i][3] << 16);
;           ((unsigned*)(smc + hy_copy_base(6)))[k] = rr[i][3];
;           ((unsigned*)(smc + hy_copy_base(7)))[k] = (rr[i][3] >> 16) | (rr[i][4] << 16);
;         }
;       }
.LBB0_668:
	s_mov_b32 s4, 0x1000706
	s_waitcnt vmcnt(0) lgkmcnt(1)
	v_perm_b32 v0, v133, v84, s4
	ds_write_b32 v132, v0 offset:27184
	ds_write_b32 v132, v84 offset:35904
	v_perm_b32 v0, v84, v85, s4
	ds_write_b32 v132, v0 offset:44656
	ds_write_b32 v132, v85 offset:53376
	s_waitcnt lgkmcnt(4)
	v_perm_b32 v0, v85, v82, s4
	ds_write_b32 v132, v0 offset:62112
	ds_write_b32 v152, v82
	v_perm_b32 v0, v82, v83, s4
	ds_write_b32 v149, v0
	s_or_b64 exec, exec, s[0:1]
	s_and_saveexec_b64 s[0:1], s[18:19]
	s_cbranch_execz .LBB0_583
.LBB0_669:
	s_mov_b32 s4, 0x1000706
	s_waitcnt vmcnt(0) lgkmcnt(1)
	v_perm_b32 v0, v138, v88, s4
	ds_write_b32 v132, v0 offset:29232
	ds_write_b32 v132, v88 offset:37952
	v_perm_b32 v0, v88, v89, s4
	ds_write_b32 v132, v0 offset:46704
	ds_write_b32 v132, v89 offset:55424
	s_waitcnt lgkmcnt(4)
	v_perm_b32 v0, v89, v86, s4
	ds_write_b32 v132, v0 offset:64160
	ds_write_b32 v155, v86
	v_perm_b32 v0, v86, v87, s4
	ds_write_b32 v153, v0
	s_or_b64 exec, exec, s[0:1]
	s_and_saveexec_b64 s[0:1], s[20:21]
	s_cbranch_execz .LBB0_584
.LBB0_670:
	s_mov_b32 s4, 0x1000706
	s_waitcnt vmcnt(0) lgkmcnt(1)
	v_perm_b32 v0, v139, v92, s4
	ds_write_b32 v132, v0 offset:31280
	ds_write_b32 v132, v92 offset:40000
	v_perm_b32 v0, v92, v93, s4
	ds_write_b32 v132, v0 offset:48752
	ds_write_b32 v132, v93 offset:57472
	s_waitcnt lgkmcnt(4)
	v_perm_b32 v0, v93, v90, s4
	ds_write_b32 v171, v0 offset:62112
	ds_write_b32 v172, v90
	v_perm_b32 v0, v90, v91, s4
	ds_write_b32 v170, v0
	s_or_b64 exec, exec, s[0:1]
	s_and_saveexec_b64 s[0:1], s[22:23]
	s_cbranch_execz .LBB0_585
.LBB0_671:
	s_mov_b32 s4, 0x1000706
	s_waitcnt vmcnt(0) lgkmcnt(1)
	v_perm_b32 v0, v140, v96, s4
	ds_write_b32 v132, v0 offset:33328
	ds_write_b32 v132, v96 offset:42048
	v_perm_b32 v0, v96, v97, s4
	ds_write_b32 v132, v0 offset:50800
	ds_write_b32 v132, v97 offset:59520
	s_waitcnt lgkmcnt(4)
	v_perm_b32 v0, v97, v94, s4
	ds_write_b32 v174, v0 offset:62112
	ds_write_b32 v175, v94
	v_perm_b32 v0, v94, v95, s4
	ds_write_b32 v173, v0
	s_or_b64 exec, exec, s[0:1]
	s_and_saveexec_b64 s[0:1], s[24:25]
	s_cbranch_execnz .LBB0_586
	s_branch .LBB0_587
